# phase 3: S5 prompt prefix loop unrolled, taking the previous segments' end states from registers already loaded together (no dependent load + drain per step)
# baseline (speedup 1.0000x reference)
; DEVINL void s5_passC_prompt(const Params& p, char* smem, int item) {
;     ...
;   for (int s2 = 0; s2 < s; ++s2) {
;     float pr = (s2 == 0) ? pw.z : pw.x, pi = (s2 == 0) ? pw.w : pw.y;
;     float2 he = hend[((size_t)bg * 7 + s2) * 64 + lane];
;     float nr = pr * hr - pi * hi + he.x, ni = pr * hi + pi * hr + he.y;
;     hr = nr; hi = ni;
;   }
.LBB0_496:
	v_pk_mul_f32 v[12:13], v[8:9], v[12:13] op_sel_hi:[1,0]
	v_add_u32_e32 v3, -1, v3
	v_pk_fma_f32 v[16:17], v[6:7], v[66:67], v[12:13] neg_lo:[0,0,1] neg_hi:[0,0,1]
	v_pk_fma_f32 v[12:13], v[6:7], v[66:67], v[12:13] op_sel_hi:[1,0,1]
	v_mov_b32_e32 v17, v13
	v_cmp_eq_u32_e32 vcc, 0, v3
	v_pk_add_f32 v[66:67], v[204:205], v[16:17]
	s_nop 0
	v_mov_b32_e32 v12, v67
	s_cbranch_vccnz .LS5P_done
	v_pk_mul_f32 v[12:13], v[8:9], v[12:13] op_sel_hi:[1,0]
	v_add_u32_e32 v3, -1, v3
	v_pk_fma_f32 v[16:17], v[6:7], v[66:67], v[12:13] neg_lo:[0,0,1] neg_hi:[0,0,1]
	v_pk_fma_f32 v[12:13], v[6:7], v[66:67], v[12:13] op_sel_hi:[1,0,1]
	v_mov_b32_e32 v17, v13
	v_cmp_eq_u32_e32 vcc, 0, v3
	v_pk_add_f32 v[66:67], v[206:207], v[16:17]
	s_nop 0
	v_mov_b32_e32 v12, v67
	s_cbranch_vccnz .LS5P_done
	v_pk_mul_f32 v[12:13], v[8:9], v[12:13] op_sel_hi:[1,0]
	v_add_u32_e32 v3, -1, v3
	v_pk_fma_f32 v[16:17], v[6:7], v[66:67], v[12:13] neg_lo:[0,0,1] neg_hi:[0,0,1]
	v_pk_fma_f32 v[12:13], v[6:7], v[66:67], v[12:13] op_sel_hi:[1,0,1]
	v_mov_b32_e32 v17, v13
	v_cmp_eq_u32_e32 vcc, 0, v3
	v_pk_add_f32 v[66:67], v[208:209], v[16:17]
	s_nop 0
	v_mov_b32_e32 v12, v67
	s_cbranch_vccnz .LS5P_done
	v_pk_mul_f32 v[12:13], v[8:9], v[12:13] op_sel_hi:[1,0]
	v_add_u32_e32 v3, -1, v3
	v_pk_fma_f32 v[16:17], v[6:7], v[66:67], v[12:13] neg_lo:[0,0,1] neg_hi:[0,0,1]
	v_pk_fma_f32 v[12:13], v[6:7], v[66:67], v[12:13] op_sel_hi:[1,0,1]
	v_mov_b32_e32 v17, v13
	v_cmp_eq_u32_e32 vcc, 0, v3
	v_pk_add_f32 v[66:67], v[210:211], v[16:17]
	s_nop 0
	v_mov_b32_e32 v12, v67
	s_cbranch_vccnz .LS5P_done
	v_pk_mul_f32 v[12:13], v[8:9], v[12:13] op_sel_hi:[1,0]
	v_add_u32_e32 v3, -1, v3
	v_pk_fma_f32 v[16:17], v[6:7], v[66:67], v[12:13] neg_lo:[0,0,1] neg_hi:[0,0,1]
	v_pk_fma_f32 v[12:13], v[6:7], v[66:67], v[12:13] op_sel_hi:[1,0,1]
	v_mov_b32_e32 v17, v13
	v_cmp_eq_u32_e32 vcc, 0, v3
	v_pk_add_f32 v[66:67], v[212:213], v[16:17]
	s_nop 0
	v_mov_b32_e32 v12, v67
	s_cbranch_vccnz .LS5P_done
	v_pk_mul_f32 v[12:13], v[8:9], v[12:13] op_sel_hi:[1,0]
	v_add_u32_e32 v3, -1, v3
	v_pk_fma_f32 v[16:17], v[6:7], v[66:67], v[12:13] neg_lo:[0,0,1] neg_hi:[0,0,1]
	v_pk_fma_f32 v[12:13], v[6:7], v[66:67], v[12:13] op_sel_hi:[1,0,1]
	v_mov_b32_e32 v17, v13
	v_cmp_eq_u32_e32 vcc, 0, v3
	v_pk_add_f32 v[66:67], v[214:215], v[16:17]
	s_nop 0
	v_mov_b32_e32 v12, v67
.LS5P_done:
	s_or_b64 exec, exec, s[0:1]
.LBB0_498:
	s_or_b64 exec, exec, s[38:39]
